# grid-sync pollers back off (s_sleep 32 between polls of the hot word); rest as v058
# speedup vs baseline: 1.0014x; 1.0014x over previous
.LBB0_18:
	s_sleep 32
	global_load_dword v2, v0, s[8:9] offset:32 sc1
	s_waitcnt vmcnt(0)
	v_and_b32_e32 v2, 0xffff0000, v2
	v_cmp_ne_u32_e64 s[4:5], v2, v1
	s_or_b64 s[10:11], s[4:5], s[10:11]
	s_andn2_b64 exec, exec, s[10:11]
	s_cbranch_execnz .LBB0_18
